# grid barrier: non-leader workgroups poll the top-level generation word directly (no per-XCD relay hop)
# speedup vs baseline: 1.1799x; 1.0124x over previous
.LBB0_77:
	s_or_b64 exec, exec, s[10:11]
	v_cvt_f32_u32_e32 v4, v2
	s_waitcnt vmcnt(0)
	v_readfirstlane_b32 s8, v3
	v_sub_u32_e32 v3, 0, v2
	v_rcp_iflag_f32_e32 v4, v4
	v_add_u32_e32 v5, s8, v1
	v_mul_f32_e32 v4, 0x4f7ffffe, v4
	v_cvt_u32_f32_e32 v4, v4
	v_mul_lo_u32 v1, v3, v4
	v_mul_hi_u32 v1, v4, v1
	v_add_u32_e32 v1, v4, v1
	v_mul_hi_u32 v1, v5, v1
	v_mul_lo_u32 v3, v1, v2
	v_sub_u32_e32 v3, v5, v3
	v_add_u32_e32 v4, 1, v1
	v_cmp_ge_u32_e32 vcc, v3, v2
	s_nop 1
	v_cndmask_b32_e32 v1, v1, v4, vcc
	v_sub_u32_e32 v4, v3, v2
	v_cndmask_b32_e32 v3, v3, v4, vcc
	v_add_u32_e32 v4, 1, v1
	v_cmp_ge_u32_e32 vcc, v3, v2
	v_add_u32_e32 v3, 1, v5
	s_nop 0
	v_cndmask_b32_e32 v1, v1, v4, vcc
	v_mul_lo_u32 v4, v2, v1
	v_add_u32_e32 v2, v4, v2
	v_cmp_ne_u32_e32 vcc, v3, v2
	s_and_saveexec_b64 s[8:9], vcc
	s_xor_b64 s[8:9], exec, s[8:9]
	s_cbranch_execz .LBB0_91
	v_readlane_b32 s14, v251, 12
	v_readlane_b32 s15, v251, 13
	v_mov_b32_e32 v0, 0
	s_nop 3
	s_add_u32 s14, s14, 0x3500
	s_addc_u32 s15, s15, 0
	global_load_dword v0, v0, s[14:15] sc1
	s_waitcnt vmcnt(0)
	v_cmp_eq_u32_e32 vcc, v0, v1
	s_and_saveexec_b64 s[10:11], vcc
	s_cbranch_execz .LBB0_90
	s_mov_b32 s12, 1
	s_mov_b64 s[16:17], 0
	v_mov_b32_e32 v0, 0
	s_branch .LBB0_81

.LBB0_154:
	s_or_b64 exec, exec, s[8:9]
	v_cvt_f32_u32_e32 v4, v2
	s_waitcnt vmcnt(0)
	v_readfirstlane_b32 s3, v3
	v_sub_u32_e32 v3, 0, v2
	v_rcp_iflag_f32_e32 v4, v4
	v_add_u32_e32 v5, s3, v1
	v_mul_f32_e32 v4, 0x4f7ffffe, v4
	v_cvt_u32_f32_e32 v4, v4
	v_mul_lo_u32 v1, v3, v4
	v_mul_hi_u32 v1, v4, v1
	v_add_u32_e32 v1, v4, v1
	v_mul_hi_u32 v1, v5, v1
	v_mul_lo_u32 v3, v1, v2
	v_sub_u32_e32 v3, v5, v3
	v_add_u32_e32 v4, 1, v1
	v_cmp_ge_u32_e32 vcc, v3, v2
	s_nop 1
	v_cndmask_b32_e32 v1, v1, v4, vcc
	v_sub_u32_e32 v4, v3, v2
	v_cndmask_b32_e32 v3, v3, v4, vcc
	v_add_u32_e32 v4, 1, v1
	v_cmp_ge_u32_e32 vcc, v3, v2
	v_add_u32_e32 v3, 1, v5
	s_nop 0
	v_cndmask_b32_e32 v1, v1, v4, vcc
	v_mul_lo_u32 v4, v2, v1
	v_add_u32_e32 v2, v4, v2
	v_cmp_ne_u32_e32 vcc, v3, v2
	s_and_saveexec_b64 s[6:7], vcc
	s_xor_b64 s[6:7], exec, s[6:7]
	s_cbranch_execz .LBB0_168
	s_waitcnt lgkmcnt(0)
	v_readlane_b32 s10, v251, 12
	v_readlane_b32 s11, v251, 13
	v_mov_b32_e32 v0, 0
	s_nop 3
	s_add_u32 s10, s10, 0x3500
	s_addc_u32 s11, s11, 0
	global_load_dword v0, v0, s[10:11] sc1
	s_waitcnt vmcnt(0)
	v_cmp_eq_u32_e32 vcc, v0, v1
	s_and_saveexec_b64 s[8:9], vcc
	s_cbranch_execz .LBB0_167
	s_mov_b32 s3, 1
	s_mov_b64 s[14:15], 0
	v_mov_b32_e32 v0, 0
	s_branch .LBB0_158

.LBB0_485:
	s_or_b64 exec, exec, s[14:15]
	v_cvt_f32_u32_e32 v4, v2
	s_waitcnt vmcnt(0)
	v_readfirstlane_b32 s3, v3
	v_sub_u32_e32 v3, 0, v2
	v_rcp_iflag_f32_e32 v4, v4
	v_add_u32_e32 v5, s3, v1
	v_mul_f32_e32 v4, 0x4f7ffffe, v4
	v_cvt_u32_f32_e32 v4, v4
	v_mul_lo_u32 v1, v3, v4
	v_mul_hi_u32 v1, v4, v1
	v_add_u32_e32 v1, v4, v1
	v_mul_hi_u32 v1, v5, v1
	v_mul_lo_u32 v3, v1, v2
	v_sub_u32_e32 v3, v5, v3
	v_add_u32_e32 v4, 1, v1
	v_cmp_ge_u32_e32 vcc, v3, v2
	s_nop 1
	v_cndmask_b32_e32 v1, v1, v4, vcc
	v_sub_u32_e32 v4, v3, v2
	v_cndmask_b32_e32 v3, v3, v4, vcc
	v_add_u32_e32 v4, 1, v1
	v_cmp_ge_u32_e32 vcc, v3, v2
	v_add_u32_e32 v3, 1, v5
	s_nop 0
	v_cndmask_b32_e32 v1, v1, v4, vcc
	v_mul_lo_u32 v4, v2, v1
	v_add_u32_e32 v2, v4, v2
	v_cmp_ne_u32_e32 vcc, v3, v2
	s_and_saveexec_b64 s[4:5], vcc
	s_xor_b64 s[10:11], exec, s[4:5]
	s_cbranch_execz .LBB0_499
	s_waitcnt lgkmcnt(0)
	v_readlane_b32 s16, v251, 12
	v_readlane_b32 s17, v251, 13
	v_mov_b32_e32 v0, 0
	s_nop 3
	s_add_u32 s16, s16, 0x3500
	s_addc_u32 s17, s17, 0
	global_load_dword v0, v0, s[16:17] sc1
	s_waitcnt vmcnt(0)
	v_cmp_eq_u32_e32 vcc, v0, v1
	s_and_saveexec_b64 s[14:15], vcc
	s_cbranch_execz .LBB0_498
	s_mov_b32 s3, 1
	s_mov_b64 s[18:19], 0
	v_mov_b32_e32 v0, 0
	s_branch .LBB0_489

.LBB0_707:
	s_or_b64 exec, exec, s[8:9]
	v_cvt_f32_u32_e32 v4, v2
	s_waitcnt vmcnt(0)
	v_readfirstlane_b32 s6, v3
	v_sub_u32_e32 v3, 0, v2
	v_rcp_iflag_f32_e32 v4, v4
	v_add_u32_e32 v5, s6, v1
	v_mul_f32_e32 v4, 0x4f7ffffe, v4
	v_cvt_u32_f32_e32 v4, v4
	v_mul_lo_u32 v1, v3, v4
	v_mul_hi_u32 v1, v4, v1
	v_add_u32_e32 v1, v4, v1
	v_mul_hi_u32 v1, v5, v1
	v_mul_lo_u32 v3, v1, v2
	v_sub_u32_e32 v3, v5, v3
	v_add_u32_e32 v4, 1, v1
	v_cmp_ge_u32_e32 vcc, v3, v2
	s_nop 1
	v_cndmask_b32_e32 v1, v1, v4, vcc
	v_sub_u32_e32 v4, v3, v2
	v_cndmask_b32_e32 v3, v3, v4, vcc
	v_add_u32_e32 v4, 1, v1
	v_cmp_ge_u32_e32 vcc, v3, v2
	v_add_u32_e32 v3, 1, v5
	s_nop 0
	v_cndmask_b32_e32 v1, v1, v4, vcc
	v_mul_lo_u32 v4, v2, v1
	v_add_u32_e32 v2, v4, v2
	v_cmp_ne_u32_e32 vcc, v3, v2
	s_and_saveexec_b64 s[6:7], vcc
	s_xor_b64 s[6:7], exec, s[6:7]
	s_cbranch_execz .LBB0_721
	s_waitcnt lgkmcnt(0)
	v_readlane_b32 s10, v251, 12
	v_readlane_b32 s11, v251, 13
	v_mov_b32_e32 v0, 0
	s_nop 3
	s_add_u32 s10, s10, 0x3500
	s_addc_u32 s11, s11, 0
	global_load_dword v0, v0, s[10:11] sc1
	s_waitcnt vmcnt(0)
	v_cmp_eq_u32_e32 vcc, v0, v1
	s_and_saveexec_b64 s[8:9], vcc
	s_cbranch_execz .LBB0_720
	s_mov_b32 s28, 1
	s_mov_b64 s[16:17], 0
	v_mov_b32_e32 v0, 0
	s_branch .LBB0_711

.LBB0_762:
	s_or_b64 exec, exec, s[8:9]
	v_cvt_f32_u32_e32 v4, v2
	s_waitcnt vmcnt(0)
	v_readfirstlane_b32 s6, v3
	v_sub_u32_e32 v3, 0, v2
	v_rcp_iflag_f32_e32 v4, v4
	v_add_u32_e32 v5, s6, v1
	v_mul_f32_e32 v4, 0x4f7ffffe, v4
	v_cvt_u32_f32_e32 v4, v4
	v_mul_lo_u32 v1, v3, v4
	v_mul_hi_u32 v1, v4, v1
	v_add_u32_e32 v1, v4, v1
	v_mul_hi_u32 v1, v5, v1
	v_mul_lo_u32 v3, v1, v2
	v_sub_u32_e32 v3, v5, v3
	v_add_u32_e32 v4, 1, v1
	v_cmp_ge_u32_e32 vcc, v3, v2
	s_nop 1
	v_cndmask_b32_e32 v1, v1, v4, vcc
	v_sub_u32_e32 v4, v3, v2
	v_cndmask_b32_e32 v3, v3, v4, vcc
	v_add_u32_e32 v4, 1, v1
	v_cmp_ge_u32_e32 vcc, v3, v2
	v_add_u32_e32 v3, 1, v5
	s_nop 0
	v_cndmask_b32_e32 v1, v1, v4, vcc
	v_mul_lo_u32 v4, v2, v1
	v_add_u32_e32 v2, v4, v2
	v_cmp_ne_u32_e32 vcc, v3, v2
	s_and_saveexec_b64 s[6:7], vcc
	s_xor_b64 s[6:7], exec, s[6:7]
	s_cbranch_execz .LBB0_776
	s_waitcnt lgkmcnt(0)
	v_readlane_b32 s10, v251, 12
	v_readlane_b32 s11, v251, 13
	v_mov_b32_e32 v0, 0
	s_nop 3
	s_add_u32 s10, s10, 0x3500
	s_addc_u32 s11, s11, 0
	global_load_dword v0, v0, s[10:11] sc1
	s_waitcnt vmcnt(0)
	v_cmp_eq_u32_e32 vcc, v0, v1
	s_and_saveexec_b64 s[8:9], vcc
	s_cbranch_execz .LBB0_775
	s_mov_b32 s30, 1
	s_mov_b64 s[18:19], 0
	v_mov_b32_e32 v0, 0
	s_branch .LBB0_766

.LBB0_873:
	s_or_b64 exec, exec, s[8:9]
	v_cvt_f32_u32_e32 v4, v2
	s_waitcnt vmcnt(0)
	v_readfirstlane_b32 s6, v3
	v_sub_u32_e32 v3, 0, v2
	v_rcp_iflag_f32_e32 v4, v4
	v_add_u32_e32 v5, s6, v1
	v_mul_f32_e32 v4, 0x4f7ffffe, v4
	v_cvt_u32_f32_e32 v4, v4
	v_mul_lo_u32 v1, v3, v4
	v_mul_hi_u32 v1, v4, v1
	v_add_u32_e32 v1, v4, v1
	v_mul_hi_u32 v1, v5, v1
	v_mul_lo_u32 v3, v1, v2
	v_sub_u32_e32 v3, v5, v3
	v_add_u32_e32 v4, 1, v1
	v_cmp_ge_u32_e32 vcc, v3, v2
	s_nop 1
	v_cndmask_b32_e32 v1, v1, v4, vcc
	v_sub_u32_e32 v4, v3, v2
	v_cndmask_b32_e32 v3, v3, v4, vcc
	v_add_u32_e32 v4, 1, v1
	v_cmp_ge_u32_e32 vcc, v3, v2
	v_add_u32_e32 v3, 1, v5
	s_nop 0
	v_cndmask_b32_e32 v1, v1, v4, vcc
	v_mul_lo_u32 v4, v2, v1
	v_add_u32_e32 v2, v4, v2
	v_cmp_ne_u32_e32 vcc, v3, v2
	s_and_saveexec_b64 s[6:7], vcc
	s_xor_b64 s[6:7], exec, s[6:7]
	s_cbranch_execz .LBB0_887
	s_waitcnt lgkmcnt(0)
	v_readlane_b32 s10, v251, 12
	v_readlane_b32 s11, v251, 13
	v_mov_b32_e32 v0, 0
	s_nop 3
	s_add_u32 s10, s10, 0x3500
	s_addc_u32 s11, s11, 0
	global_load_dword v0, v0, s[10:11] sc1
	s_waitcnt vmcnt(0)
	v_cmp_eq_u32_e32 vcc, v0, v1
	s_and_saveexec_b64 s[8:9], vcc
	s_cbranch_execz .LBB0_886
	s_mov_b32 s28, 1
	s_mov_b64 s[18:19], 0
	v_mov_b32_e32 v0, 0
	s_branch .LBB0_877

.LBB0_945:
	s_or_b64 exec, exec, s[8:9]
	v_cvt_f32_u32_e32 v4, v2
	s_waitcnt vmcnt(0)
	v_readfirstlane_b32 s3, v3
	v_sub_u32_e32 v3, 0, v2
	v_rcp_iflag_f32_e32 v4, v4
	v_add_u32_e32 v5, s3, v1
	v_mul_f32_e32 v4, 0x4f7ffffe, v4
	v_cvt_u32_f32_e32 v4, v4
	v_mul_lo_u32 v1, v3, v4
	v_mul_hi_u32 v1, v4, v1
	v_add_u32_e32 v1, v4, v1
	v_mul_hi_u32 v1, v5, v1
	v_mul_lo_u32 v3, v1, v2
	v_sub_u32_e32 v3, v5, v3
	v_add_u32_e32 v4, 1, v1
	v_cmp_ge_u32_e32 vcc, v3, v2
	s_nop 1
	v_cndmask_b32_e32 v1, v1, v4, vcc
	v_sub_u32_e32 v4, v3, v2
	v_cndmask_b32_e32 v3, v3, v4, vcc
	v_add_u32_e32 v4, 1, v1
	v_cmp_ge_u32_e32 vcc, v3, v2
	v_add_u32_e32 v3, 1, v5
	s_nop 0
	v_cndmask_b32_e32 v1, v1, v4, vcc
	v_mul_lo_u32 v4, v2, v1
	v_add_u32_e32 v2, v4, v2
	v_cmp_ne_u32_e32 vcc, v3, v2
	s_and_saveexec_b64 s[6:7], vcc
	s_xor_b64 s[6:7], exec, s[6:7]
	s_cbranch_execz .LBB0_959
	s_waitcnt lgkmcnt(0)
	v_readlane_b32 s10, v251, 12
	v_readlane_b32 s11, v251, 13
	v_mov_b32_e32 v0, 0
	s_nop 3
	s_add_u32 s10, s10, 0x3500
	s_addc_u32 s11, s11, 0
	global_load_dword v0, v0, s[10:11] sc1
	s_waitcnt vmcnt(0)
	v_cmp_eq_u32_e32 vcc, v0, v1
	s_and_saveexec_b64 s[8:9], vcc
	s_cbranch_execz .LBB0_958
	s_mov_b32 s3, 1
	s_mov_b64 s[12:13], 0
	v_mov_b32_e32 v0, 0
	s_branch .LBB0_949
